# M1 stores the within-chunk log-forget-gate cumsum (f32, in the gate buffer slot of f_pre, no longer needed); M3 reuses it instead of recomputing log-sigmoid and the scan on its serial wave-0 path
# baseline (speedup 1.0000x reference)
; __device__ __forceinline__ float wave_incl_sum(float v, int lane) {
; #pragma unroll
;     for (int o = 1; o < 64; o <<= 1) { const float t = __shfl_up(v, o); if (lane >= o) v += t; }
;     return v;
; }
; __device__ __forceinline__ float wave_incl_max(float v, int lane) {
; #pragma unroll
;     for (int o = 1; o < 64; o <<= 1) { const float t = __shfl_up(v, o); if (lane >= o) v = fmaxf(v, t); }
;     return v;
; }
; __device__ __forceinline__ float log_sigmoid_f(float x) { return fminf(x, 0.f) - log1pf(expf(-fabsf(x))); }
; __device__ __forceinline__ void m1_phase(const Params& p, unsigned char* ldsg, int G) {
;     ...
;         const int c = r >> 1, h = 2 * (r & 1) + half, u = c * 4 + h, t0 = c * CL;
;         if (hw == 0) {
;             const float ig = GATES[(size_t)(t0 + lane) * 8 + h], fp = GATES[(size_t)(t0 + lane) * 8 + 4 + h];
;             const float b = wave_incl_sum(log_sigmoid_f(fp), lane);
;             const float g = __shfl(b, 63);
;             const float a = g - b + ig;
;             const float amax = wave_max(a);
;             sW[lane] = expf(a - amax);
;             if (lane == 0) { GARR[h * NCH + c] = g; AMAXARR[h * NCH + c] = amax; }
.LBB0_611:
	s_lshl_b32 s0, s82, 1
	s_ashr_i32 s83, s82, 1
	s_and_b32 s0, s0, 2
	s_add_i32 s44, s0, s2
	s_andn2_b64 vcc, exec, s[4:5]
	s_lshl_b32 s22, s83, 6
	s_cbranch_vccnz .LBB0_615
	v_or_b32_e32 v0, s22, v153
	v_ashrrev_i32_e32 v1, 31, v0
	v_lshlrev_b64 v[0:1], 5, v[0:1]
	s_ashr_i32 s45, s44, 31
	v_lshl_add_u64 v[0:1], s[54:55], 0, v[0:1]
	v_lshl_add_u64 v[0:1], s[44:45], 2, v[0:1]
	global_load_dword v2, v[0:1], off offset:16
	global_load_dword v5, v[0:1], off
	v_mov_b64_e32 v[228:229], v[0:1]
	s_mov_b32 s0, 0xb2a5705f
	v_and_b32_e32 v3, 64, v144
	v_add_u32_e32 v4, -1, v144
	s_mov_b32 s1, 0x42ce8ed0
	v_cmp_lt_i32_e32 vcc, v4, v3
	s_mov_b32 s23, 0xc2b17218
	s_mov_b32 s24, 0x3f2aaaab
	v_cndmask_b32_e32 v4, v4, v144, vcc
	s_mov_b32 s25, 0x7f800000
	v_lshlrev_b32_e32 v4, 2, v4
	s_waitcnt vmcnt(1)
	v_mul_f32_e64 v0, |v2|, s3
	v_fma_f32 v1, |v2|, s3, -v0
	v_rndne_f32_e32 v6, v0
	v_fma_f32 v1, |v2|, s0, v1
	v_sub_f32_e32 v0, v0, v6
	v_add_f32_e32 v0, v0, v1
	v_cvt_i32_f32_e32 v6, v6
	v_exp_f32_e32 v0, v0
	v_cmp_ngt_f32_e64 vcc, |v2|, s1
	v_max_f32_e32 v1, v2, v2
	v_min_f32_e32 v7, 0, v1
	v_ldexp_f32 v0, v0, v6
	v_cndmask_b32_e32 v0, 0, v0, vcc
	v_cmp_nlt_f32_e64 vcc, |v2|, s23
	s_nop 1
	v_cndmask_b32_e32 v2, v143, v0, vcc
	v_add_f32_e32 v6, 1.0, v2
	v_add_f32_e32 v8, -1.0, v6
	v_frexp_mant_f32_e32 v9, v6
	v_cvt_f64_f32_e32 v[0:1], v6
	v_sub_f32_e32 v10, v8, v6
	v_frexp_exp_i32_f64_e32 v0, v[0:1]
	v_cmp_gt_f32_e32 vcc, s24, v9
	v_sub_f32_e32 v8, v2, v8
	v_add_f32_e32 v1, 1.0, v10
	v_subbrev_co_u32_e32 v0, vcc, 0, v0, vcc
	v_add_f32_e32 v1, v8, v1
	v_sub_u32_e32 v8, 0, v0
	v_cvt_f32_i32_e32 v0, v0
	v_ldexp_f32 v6, v6, v8
	v_ldexp_f32 v1, v1, v8
	v_add_f32_e32 v8, -1.0, v6
	v_add_f32_e32 v9, 1.0, v6
	v_add_f32_e32 v10, 1.0, v8
	v_add_f32_e32 v11, -1.0, v9
	v_sub_f32_e32 v10, v6, v10
	v_sub_f32_e32 v6, v6, v11
	v_mul_f32_e32 v11, 0x3f317218, v0
	v_add_f32_e32 v10, v1, v10
	v_add_f32_e32 v1, v1, v6
	v_fma_f32 v6, v0, s33, -v11
	v_add_f32_e32 v12, v8, v10
	v_add_f32_e32 v13, v9, v1
	v_fmac_f32_e32 v6, 0xb102e308, v0
	v_sub_f32_e32 v0, v8, v12
	v_sub_f32_e32 v8, v9, v13
	v_rcp_f32_e32 v9, v13
	v_add_f32_e32 v14, v11, v6
	v_add_f32_e32 v1, v1, v8
	v_sub_f32_e32 v8, v14, v11
	v_sub_f32_e32 v6, v6, v8
	v_mul_f32_e32 v8, v12, v9
	v_add_f32_e32 v0, v10, v0
	v_mul_f32_e32 v10, v13, v8
	v_fma_f32 v11, v8, v13, -v10
	v_fmac_f32_e32 v11, v8, v1
	v_add_f32_e32 v15, v10, v11
	v_sub_f32_e32 v16, v12, v15
	v_sub_f32_e32 v10, v15, v10
	v_sub_f32_e32 v12, v12, v16
	v_sub_f32_e32 v10, v10, v11
	v_sub_f32_e32 v11, v12, v15
	v_add_f32_e32 v0, v0, v11
	v_add_f32_e32 v0, v10, v0
	v_add_f32_e32 v10, v16, v0
	v_mul_f32_e32 v11, v9, v10
	v_sub_f32_e32 v12, v16, v10
	v_mul_f32_e32 v15, v13, v11
	v_add_f32_e32 v0, v0, v12
	v_add_f32_e32 v12, v8, v11
	v_fma_f32 v13, v11, v13, -v15
	v_sub_f32_e32 v8, v12, v8
	v_fmac_f32_e32 v13, v11, v1
	v_sub_f32_e32 v1, v11, v8
	v_add_f32_e32 v8, v15, v13
	v_sub_f32_e32 v11, v8, v15
	v_sub_f32_e32 v15, v10, v8
	v_sub_f32_e32 v10, v10, v15
	v_sub_f32_e32 v8, v10, v8
	v_sub_f32_e32 v11, v11, v13
	v_add_f32_e32 v0, v0, v8
	v_add_f32_e32 v0, v11, v0
	v_add_f32_e32 v0, v15, v0
	v_mul_f32_e32 v0, v9, v0
	v_add_f32_e32 v0, v1, v0
	v_add_f32_e32 v1, v12, v0
	v_mul_f32_e32 v8, v1, v1
	v_fmamk_f32 v11, v8, 0x3e9b6dac, v141
	v_sub_f32_e32 v9, v1, v12
	v_ldexp_f32 v10, v1, 1
	v_mul_f32_e32 v1, v1, v8
	v_fmaak_f32 v8, v8, v11, 0x3f2aaada
	v_mul_f32_e32 v1, v1, v8
	v_add_f32_e32 v8, v10, v1
	v_sub_f32_e32 v0, v0, v9
	v_sub_f32_e32 v9, v8, v10
	v_ldexp_f32 v0, v0, 1
	v_sub_f32_e32 v1, v1, v9
	v_add_f32_e32 v0, v0, v1
	v_add_f32_e32 v1, v8, v0
	v_sub_f32_e32 v8, v1, v8
	v_add_f32_e32 v9, v14, v1
	v_sub_f32_e32 v0, v0, v8
	v_sub_f32_e32 v8, v9, v14
	v_sub_f32_e32 v10, v9, v8
	v_sub_f32_e32 v1, v1, v8
	v_add_f32_e32 v8, v6, v0
	v_sub_f32_e32 v10, v14, v10
	v_sub_f32_e32 v11, v8, v6
	v_add_f32_e32 v1, v1, v10
	v_sub_f32_e32 v10, v8, v11
	v_sub_f32_e32 v0, v0, v11
	v_sub_f32_e32 v6, v6, v10
	v_add_f32_e32 v1, v8, v1
	v_add_f32_e32 v0, v0, v6
	v_add_f32_e32 v6, v9, v1
	v_sub_f32_e32 v8, v6, v9
	v_sub_f32_e32 v1, v1, v8
	v_add_f32_e32 v0, v0, v1
	v_add_f32_e32 v0, v6, v0
	v_cmp_neq_f32_e32 vcc, s25, v2
	s_nop 1
	v_cndmask_b32_e32 v0, v143, v0, vcc
	v_cmp_lt_f32_e64 vcc, |v2|, s43
	s_nop 1
	v_cndmask_b32_e32 v0, v0, v2, vcc
	v_sub_f32_e32 v0, v7, v0
	s_nop 1
	v_add_f32_dpp v0, v0, v0 row_shr:1 row_mask:0xf bank_mask:0xf bound_ctrl:0
	s_nop 1
	v_add_f32_dpp v0, v0, v0 row_shr:2 row_mask:0xf bank_mask:0xf bound_ctrl:0
	s_nop 1
	v_add_f32_dpp v0, v0, v0 row_shr:4 row_mask:0xf bank_mask:0xf bound_ctrl:0
	s_nop 1
	v_add_f32_dpp v0, v0, v0 row_shr:8 row_mask:0xf bank_mask:0xf bound_ctrl:0
	s_nop 1
	v_add_f32_dpp v0, v0, v0 row_bcast:15 row_mask:0xa bank_mask:0xf
	s_nop 1
	v_add_f32_dpp v0, v0, v0 row_bcast:31 row_mask:0xc bank_mask:0xf
	s_nop 0
	global_store_dword v[228:229], v0, off offset:16
	s_nop 1
	v_readlane_b32 s98, v0, 63
	s_waitcnt vmcnt(0)
	s_nop 1
	v_sub_f32_e32 v1, s98, v0
	v_add_f32_e32 v4, v5, v1
	v_mov_b32_e32 v1, v4
	s_nop 1
	v_max_f32_dpp v1, v1, v1 row_shr:1 row_mask:0xf bank_mask:0xf
	s_nop 1
	v_max_f32_dpp v1, v1, v1 row_shr:2 row_mask:0xf bank_mask:0xf
	s_nop 1
	v_max_f32_dpp v1, v1, v1 row_shr:4 row_mask:0xf bank_mask:0xf
	s_nop 1
	v_max_f32_dpp v1, v1, v1 row_shr:8 row_mask:0xf bank_mask:0xf
	s_nop 1
	v_max_f32_dpp v1, v1, v1 row_bcast:15 row_mask:0xa bank_mask:0xf
	s_nop 1
	v_max_f32_dpp v1, v1, v1 row_bcast:31 row_mask:0xc bank_mask:0xf
	s_nop 1
	v_readlane_b32 s99, v1, 63
	s_nop 2
	v_mov_b32_e32 v1, s99
	v_mov_b32_e32 v0, s98
	v_sub_f32_e32 v2, v4, v1
	v_mul_f32_e32 v3, 0x3fb8aa3b, v2
	v_fma_f32 v4, v2, s46, -v3
	v_rndne_f32_e32 v5, v3
	v_fmac_f32_e32 v4, 0x32a5705f, v2
	v_sub_f32_e32 v3, v3, v5
	v_add_f32_e32 v3, v3, v4
	v_cvt_i32_f32_e32 v5, v5
	v_exp_f32_e32 v3, v3
	v_cmp_ngt_f32_e32 vcc, s47, v2
	v_ldexp_f32 v3, v3, v5
	s_nop 0
	v_cndmask_b32_e32 v3, 0, v3, vcc
	v_cmp_nlt_f32_e32 vcc, s62, v2
	s_nop 1
	v_cndmask_b32_e32 v2, v143, v3, vcc
	ds_write_b32 v65, v2 offset:36864
	s_and_saveexec_b64 s[0:1], s[16:17]
	s_cbranch_execz .LBB0_614
	s_lshl_b32 s23, s44, 8
	s_add_i32 s24, s23, s83
	s_ashr_i32 s25, s24, 31
	s_lshl_b64 s[24:25], s[24:25], 2
	s_add_u32 s26, s34, s24
	s_addc_u32 s27, s35, s25
	s_add_u32 s24, s36, s24
	s_addc_u32 s25, s37, s25
	global_store_dword v67, v0, s[26:27]
	global_store_dword v67, v1, s[24:25]

; __device__ __forceinline__ float log_sigmoid_f(float x) { return fminf(x, 0.f) - log1pf(expf(-fabsf(x))); }
; __device__ __forceinline__ void m3_phase(const Params& p, unsigned char* ldsg, int G) {
;     ...
;             if (wave == 0) {
;                 const float b = wave_incl_sum(log_sigmoid_f(g_fp), lane);
;                 const float uu = g_ig - b;
;                 const float U = wave_incl_max(uu, lane);
;                 const float mp = g_mp;
;                 const float M = fmaxf(mp, U);
;                 sU[lane] = uu; sM[lane] = M; sIW[lane] = expf(mp - M); sEMT[lane] = expf(-(b + M)); sRS[lane] = 0.f; sHS[lane] = 0.f;
.LBB0_1123:
	s_andn2_b64 vcc, exec, s[44:45]
	s_cbranch_vccnz .LBB0_1125
	s_waitcnt vmcnt(3)
	v_mov_b32_e32 v48, v193
	v_sub_f32_e32 v55, v130, v48
	v_mov_b32_e32 v49, v55
	s_nop 1
	v_max_f32_dpp v49, v49, v49 row_shr:1 row_mask:0xf bank_mask:0xf
	s_nop 1
	v_max_f32_dpp v49, v49, v49 row_shr:2 row_mask:0xf bank_mask:0xf
	s_nop 1
	v_max_f32_dpp v49, v49, v49 row_shr:4 row_mask:0xf bank_mask:0xf
	s_nop 1
	v_max_f32_dpp v49, v49, v49 row_shr:8 row_mask:0xf bank_mask:0xf
	s_nop 1
	v_max_f32_dpp v49, v49, v49 row_bcast:15 row_mask:0xa bank_mask:0xf
	s_nop 1
	v_max_f32_dpp v49, v49, v49 row_bcast:31 row_mask:0xc bank_mask:0xf
	s_waitcnt vmcnt(2)
	v_max_f32_e32 v50, v111, v111
	v_max_f32_e32 v49, v50, v49
	v_sub_f32_e32 v50, v111, v49
	v_mul_f32_e32 v51, 0x3fb8aa3b, v50
	v_fma_f32 v52, v50, s63, -v51
	v_rndne_f32_e32 v53, v51
	v_fmac_f32_e32 v52, 0x32a5705f, v50
	v_sub_f32_e32 v51, v51, v53
	v_add_f32_e32 v51, v51, v52
	v_exp_f32_e32 v51, v51
	v_cvt_i32_f32_e32 v52, v53
	v_add_f32_e32 v48, v48, v49
	ds_write_b32 v91, v55
	ds_write_b32 v93, v49
	v_mul_f32_e32 v49, 0xbfb8aa3b, v48
	v_ldexp_f32 v51, v51, v52
	v_fma_f32 v52, v48, s60, -v49
	v_rndne_f32_e32 v53, v49
	v_fmac_f32_e32 v52, 0xb2a5705f, v48
	v_sub_f32_e32 v49, v49, v53
	v_add_f32_e32 v49, v49, v52
	v_exp_f32_e32 v49, v49
	v_cvt_i32_f32_e32 v52, v53
	v_cmp_ngt_f32_e32 vcc, s64, v50
	v_ldexp_f32 v49, v49, v52
	s_nop 0
	v_cndmask_b32_e32 v51, 0, v51, vcc
	v_cmp_nlt_f32_e32 vcc, s65, v50
	s_nop 1
	v_cndmask_b32_e32 v50, v190, v51, vcc
	v_cmp_nlt_f32_e32 vcc, s61, v48
	ds_write_b32 v94, v50
	s_nop 0
	v_cndmask_b32_e32 v49, 0, v49, vcc
	v_cmp_ngt_f32_e32 vcc, s62, v48
	s_nop 1
	v_cndmask_b32_e32 v48, v190, v49, vcc
	ds_write_b32 v95, v48
	ds_write_b32 v96, v81
	ds_write_b32 v97, v81
